# P1: CUs that own a memory-KV unit hand their 5th FFN1 tile to idle CUs 144-159 (static order remap); plus v2 P0 changes
# speedup vs baseline: 1.0177x; 1.0061x over previous
;     __device__ __forceinline__ bool next(int i, Unit& u) const { if (i) return false; u.pm = pm; u.pn = pn; return true; }
;     __host__ __device__ __forceinline__ bool next(int i, Unit& u) const {
;         const long L = (long)i * G + c; if (L >= nwg) return false;
;         int wgid = (int)L; { const int q = nwg / NXCD, r = nwg % NXCD, xcd = wgid % NXCD, off = wgid / NXCD; wgid = (xcd < r ? xcd * (q + 1) : r * (q + 1) + (xcd - r) * q) + off; }
;         const int nig = WGM * nN, gid = wgid / nig, fm = gid * WGM, gsz = (nM - fm) < WGM ? (nM - fm) : WGM;
;         u.pm = fm + ((wgid % nig) % gsz); u.pn = (wgid % nig) / gsz; return true;
; template <class Epi, class Sched, bool ALIGN_EPI = false, bool SP2 = false>
; __device__ __forceinline__ void gemm_phase(PG8_LAS unsigned char* lds, const Gemm g, const Sched& S, const Epi& E) {
;     ...
;         const bool has_next = S.next(ui + 1, nxt);
;         const char* nA = has_next ? (const char*)g.A + (size_t)nxt.pm * tstepA + (size_t)nxt.pn * g.a_pn_off * 2 : cA; const char* nB = has_next ? (const char*)g.Bt + (size_t)nxt.pn * tstepB : cB;
.LBB0_301:
	s_add_i32 s72, s72, 1
	s_mul_i32 s2, s72, s71
	s_mul_hi_u32 s3, s72, s34
	s_add_i32 s3, s3, s2
	s_mul_i32 s2, s72, s34
	s_add_u32 s6, s2, s38
	s_addc_u32 s7, s3, s62
	s_cmpk_lg_u32 s34, 0x100
	s_cbranch_scc1 .Lkv_skip
	s_cmpk_lt_u32 s38, 0x80
	s_cbranch_scc1 .Lkv_skip
	s_cmpk_gt_u32 s38, 0x9f
	s_cbranch_scc1 .Lkv_skip
	s_cmpk_lt_u32 s38, 0x90
	s_cbranch_scc0 .Lkv_hi
	s_cmpk_eq_u32 s72, 4
	s_cbranch_scc0 .Lkv_skip
	s_movk_i32 s6, 0x7fff
	s_mov_b32 s7, 0
	s_branch .Lkv_skip
.Lkv_hi:
	s_cmpk_eq_u32 s72, 5
	s_cbranch_scc0 .Lkv_skip
	s_add_i32 s6, s38, 0x3f0
	s_mov_b32 s7, 0
.Lkv_skip:
	v_cmp_gt_i64_e32 vcc, s[6:7], v[200:201]
	v_cmp_lt_i64_e64 s[2:3], s[6:7], v[198:199]
	s_cbranch_vccnz .LBB0_303
	s_ashr_i32 s7, s6, 31
	s_lshr_b32 s7, s7, 29
	s_add_i32 s7, s6, s7
	s_ashr_i32 s10, s7, 3
	s_and_b32 s7, s7, -8
	s_sub_i32 s6, s6, s7
	s_cmp_lt_i32 s6, 0
	s_movk_i32 s7, 0xb1
	s_cselect_b32 s7, s7, 0xb0
	s_mul_i32 s6, s6, s7
	s_add_i32 s6, s6, s10
	s_mul_hi_i32 s7, s6, 0x2e8ba2e9
	s_lshr_b32 s10, s7, 31
	s_ashr_i32 s7, s7, 5
	s_add_i32 s7, s7, s10
	s_lshl_b32 s11, s7, 3
	s_sub_i32 s10, 64, s11
	s_min_i32 s12, s10, 8
	s_abs_i32 s10, s12
	v_cvt_f32_u32_e32 v0, s10
	s_sub_i32 s14, 0, s10
	s_mulk_i32 s7, 0xb0
	s_sub_i32 s6, s6, s7
	v_rcp_iflag_f32_e32 v0, v0
	s_abs_i32 s7, s6
	s_xor_b32 s13, s6, s12
	s_ashr_i32 s13, s13, 31
	v_mul_f32_e32 v0, 0x4f7ffffe, v0
	v_cvt_u32_f32_e32 v0, v0
	s_nop 0
	v_readfirstlane_b32 s15, v0
	s_mul_i32 s14, s14, s15
	s_mul_hi_u32 s14, s15, s14
	s_add_i32 s15, s15, s14
	s_mul_hi_u32 s14, s7, s15
	s_mul_i32 s15, s14, s10
	s_sub_i32 s7, s7, s15
	s_add_i32 s16, s14, 1
	s_sub_i32 s15, s7, s10
	s_cmp_ge_u32 s7, s10
	s_cselect_b32 s14, s16, s14
	s_cselect_b32 s7, s15, s7
	s_add_i32 s15, s14, 1
	s_cmp_ge_u32 s7, s10
	s_cselect_b32 s7, s15, s14
	s_xor_b32 s7, s7, s13
	s_sub_i32 s10, s7, s13
	s_mul_i32 s7, s10, s12
	s_sub_i32 s6, s6, s7
	s_add_i32 s12, s11, s6
